# P5 GLU output stores sc1, on top of v111
# baseline (speedup 1.0000x reference)
.LBB0_652:
	v_mul_f32_e32 v116, 0xbfb8aa3b, v116
	v_mul_f32_e32 v112, 0xbfb8aa3b, v112
	v_exp_f32_e32 v116, v116
	v_exp_f32_e32 v145, v112
	v_mul_f32_e32 v117, 0xbfb8aa3b, v117
	v_mul_f32_e32 v113, 0xbfb8aa3b, v113
	v_add_f32_e32 v112, 1.0, v116
	v_add_f32_e32 v116, 1.0, v145
	v_exp_f32_e32 v117, v117
	v_exp_f32_e32 v145, v113
	v_mul_f32_e32 v118, 0xbfb8aa3b, v118
	v_mul_f32_e32 v114, 0xbfb8aa3b, v114
	v_add_f32_e32 v113, 1.0, v117
	v_add_f32_e32 v117, 1.0, v145
	v_exp_f32_e32 v118, v118
	v_exp_f32_e32 v145, v114
	v_mul_f32_e32 v119, 0xbfb8aa3b, v119
	v_mul_f32_e32 v115, 0xbfb8aa3b, v115
	v_add_f32_e32 v114, 1.0, v118
	v_add_f32_e32 v118, 1.0, v145
	v_exp_f32_e32 v119, v119
	v_exp_f32_e32 v145, v115
	v_rcp_f32_e32 v112, v112
	v_rcp_f32_e32 v113, v113
	v_add_f32_e32 v115, 1.0, v119
	v_add_f32_e32 v119, 1.0, v145
	v_rcp_f32_e32 v116, v116
	v_rcp_f32_e32 v117, v117
	v_rcp_f32_e32 v114, v114
	v_rcp_f32_e32 v118, v118
	v_rcp_f32_e32 v115, v115
	v_rcp_f32_e32 v119, v119
	v_lshl_add_u32 v144, s20, 8, v146
	v_lshl_add_u32 v152, s43, 7, v148
	v_pk_mul_f32 v[112:113], v[124:125], v[112:113]
	v_ashrrev_i32_e32 v145, 31, v144
	v_ashrrev_i32_e32 v153, 31, v152
	v_pk_mul_f32 v[116:117], v[120:121], v[116:117]
	v_pk_mul_f32 v[120:121], v[126:127], v[114:115]
	v_pk_mul_f32 v[118:119], v[122:123], v[118:119]
	v_cvt_pk_bf16_f32 v114, v112, v113
	v_lshlrev_b64 v[112:113], 11, v[144:145]
	v_cvt_pk_bf16_f32 v116, v116, v117
	v_cvt_pk_bf16_f32 v117, v118, v119
	v_lshl_add_u64 v[112:113], s[82:83], 0, v[112:113]
	v_lshlrev_b64 v[118:119], 1, v[152:153]
	v_cvt_pk_bf16_f32 v115, v120, v121
	v_lshl_add_u64 v[112:113], v[112:113], 0, v[118:119]
	v_mul_f32_e32 v101, 0xbfb8aa3b, v101
	v_mul_f32_e32 v97, 0xbfb8aa3b, v97
	global_store_dwordx4 v[112:113], v[114:117], off sc1
	v_exp_f32_e32 v101, v101
	v_mul_f32_e32 v102, 0xbfb8aa3b, v102
	v_exp_f32_e32 v114, v97
	v_mul_f32_e32 v98, 0xbfb8aa3b, v98
	v_mul_f32_e32 v100, 0xbfb8aa3b, v100
	v_mul_f32_e32 v96, 0xbfb8aa3b, v96
	v_add_f32_e32 v97, 1.0, v101
	v_add_f32_e32 v101, 1.0, v114
	v_exp_f32_e32 v102, v102
	v_exp_f32_e32 v114, v98
	v_exp_f32_e32 v100, v100
	v_exp_f32_e32 v120, v96
	v_mul_f32_e32 v103, 0xbfb8aa3b, v103
	v_exp_f32_e32 v103, v103
	v_mul_f32_e32 v99, 0xbfb8aa3b, v99
	v_add_f32_e32 v98, 1.0, v102
	v_add_f32_e32 v102, 1.0, v114
	v_exp_f32_e32 v114, v99
	v_add_f32_e32 v96, 1.0, v100
	v_add_f32_e32 v100, 1.0, v120
	v_rcp_f32_e32 v100, v100
	v_rcp_f32_e32 v101, v101
	v_add_f32_e32 v99, 1.0, v103
	v_rcp_f32_e32 v96, v96
	v_rcp_f32_e32 v97, v97
	v_rcp_f32_e32 v98, v98
	v_rcp_f32_e32 v99, v99
	v_add_f32_e32 v103, 1.0, v114
	v_rcp_f32_e32 v102, v102
	v_rcp_f32_e32 v103, v103
	v_pk_mul_f32 v[100:101], v[104:105], v[100:101]
	v_or_b32_e32 v104, 16, v144
	v_pk_mul_f32 v[96:97], v[108:109], v[96:97]
	v_pk_mul_f32 v[98:99], v[110:111], v[98:99]
	v_ashrrev_i32_e32 v105, 31, v104
	v_cvt_pk_bf16_f32 v96, v96, v97
	v_cvt_pk_bf16_f32 v97, v98, v99
	v_cvt_pk_bf16_f32 v98, v100, v101
	v_lshlrev_b64 v[100:101], 11, v[104:105]
	v_pk_mul_f32 v[102:103], v[106:107], v[102:103]
	v_lshl_add_u64 v[100:101], s[82:83], 0, v[100:101]
	v_cvt_pk_bf16_f32 v99, v102, v103
	v_lshl_add_u64 v[100:101], v[100:101], 0, v[118:119]
	v_mul_f32_e32 v85, 0xbfb8aa3b, v85
	v_mul_f32_e32 v81, 0xbfb8aa3b, v81
	global_store_dwordx4 v[100:101], v[96:99], off sc1
	v_exp_f32_e32 v85, v85
	v_mul_f32_e32 v86, 0xbfb8aa3b, v86
	v_exp_f32_e32 v96, v81
	v_mul_f32_e32 v82, 0xbfb8aa3b, v82
	v_mul_f32_e32 v84, 0xbfb8aa3b, v84
	v_mul_f32_e32 v80, 0xbfb8aa3b, v80
	v_add_f32_e32 v81, 1.0, v85
	v_add_f32_e32 v85, 1.0, v96
	v_exp_f32_e32 v86, v86
	v_exp_f32_e32 v96, v82
	v_exp_f32_e32 v84, v84
	v_exp_f32_e32 v102, v80
	v_mul_f32_e32 v87, 0xbfb8aa3b, v87
	v_exp_f32_e32 v87, v87
	v_mul_f32_e32 v83, 0xbfb8aa3b, v83
	v_add_f32_e32 v82, 1.0, v86
	v_add_f32_e32 v86, 1.0, v96
	v_exp_f32_e32 v96, v83
	v_add_f32_e32 v80, 1.0, v84
	v_add_f32_e32 v84, 1.0, v102
	v_rcp_f32_e32 v84, v84
	v_rcp_f32_e32 v85, v85
	v_add_f32_e32 v83, 1.0, v87
	v_rcp_f32_e32 v80, v80
	v_rcp_f32_e32 v81, v81
	v_rcp_f32_e32 v82, v82
	v_rcp_f32_e32 v83, v83
	v_add_f32_e32 v87, 1.0, v96
	v_rcp_f32_e32 v86, v86
	v_rcp_f32_e32 v87, v87
	v_pk_mul_f32 v[84:85], v[88:89], v[84:85]
	v_or_b32_e32 v88, 32, v144
	v_pk_mul_f32 v[80:81], v[92:93], v[80:81]
	v_pk_mul_f32 v[82:83], v[94:95], v[82:83]
	v_ashrrev_i32_e32 v89, 31, v88
	v_cvt_pk_bf16_f32 v80, v80, v81
	v_cvt_pk_bf16_f32 v81, v82, v83
	v_cvt_pk_bf16_f32 v82, v84, v85
	v_lshlrev_b64 v[84:85], 11, v[88:89]
	v_pk_mul_f32 v[86:87], v[90:91], v[86:87]
	v_lshl_add_u64 v[84:85], s[82:83], 0, v[84:85]
	v_cvt_pk_bf16_f32 v83, v86, v87
	v_lshl_add_u64 v[84:85], v[84:85], 0, v[118:119]
	v_mul_f32_e32 v69, 0xbfb8aa3b, v69
	v_mul_f32_e32 v65, 0xbfb8aa3b, v65
	global_store_dwordx4 v[84:85], v[80:83], off sc1
	v_exp_f32_e32 v69, v69
	v_mul_f32_e32 v70, 0xbfb8aa3b, v70
	v_exp_f32_e32 v80, v65
	v_mul_f32_e32 v66, 0xbfb8aa3b, v66
	v_mul_f32_e32 v68, 0xbfb8aa3b, v68
	v_mul_f32_e32 v64, 0xbfb8aa3b, v64
	v_add_f32_e32 v65, 1.0, v69
	v_add_f32_e32 v69, 1.0, v80
	v_exp_f32_e32 v70, v70
	v_exp_f32_e32 v80, v66
	v_exp_f32_e32 v68, v68
	v_exp_f32_e32 v86, v64
	v_mul_f32_e32 v71, 0xbfb8aa3b, v71
	v_exp_f32_e32 v71, v71
	v_mul_f32_e32 v67, 0xbfb8aa3b, v67
	v_add_f32_e32 v66, 1.0, v70
	v_add_f32_e32 v70, 1.0, v80
	v_exp_f32_e32 v80, v67
	v_add_f32_e32 v64, 1.0, v68
	v_add_f32_e32 v68, 1.0, v86
	v_rcp_f32_e32 v68, v68
	v_rcp_f32_e32 v69, v69
	v_add_f32_e32 v67, 1.0, v71
	v_rcp_f32_e32 v64, v64
	v_rcp_f32_e32 v65, v65
	v_rcp_f32_e32 v66, v66
	v_rcp_f32_e32 v67, v67
	v_add_f32_e32 v71, 1.0, v80
	v_rcp_f32_e32 v70, v70
	v_rcp_f32_e32 v71, v71
	v_pk_mul_f32 v[68:69], v[72:73], v[68:69]
	v_or_b32_e32 v72, 48, v144
	v_pk_mul_f32 v[64:65], v[76:77], v[64:65]
	v_pk_mul_f32 v[66:67], v[78:79], v[66:67]
	v_ashrrev_i32_e32 v73, 31, v72
	v_cvt_pk_bf16_f32 v64, v64, v65
	v_cvt_pk_bf16_f32 v65, v66, v67
	v_cvt_pk_bf16_f32 v66, v68, v69
	v_lshlrev_b64 v[68:69], 11, v[72:73]
	v_pk_mul_f32 v[70:71], v[74:75], v[70:71]
	v_lshl_add_u64 v[68:69], s[82:83], 0, v[68:69]
	v_cvt_pk_bf16_f32 v67, v70, v71
	v_lshl_add_u64 v[68:69], v[68:69], 0, v[118:119]
	v_mul_f32_e32 v53, 0xbfb8aa3b, v53
	v_mul_f32_e32 v49, 0xbfb8aa3b, v49
	global_store_dwordx4 v[68:69], v[64:67], off sc1
	v_exp_f32_e32 v53, v53
	v_mul_f32_e32 v54, 0xbfb8aa3b, v54
	v_exp_f32_e32 v64, v49
	v_mul_f32_e32 v50, 0xbfb8aa3b, v50
	v_add_f32_e32 v49, 1.0, v53
	v_exp_f32_e32 v54, v54
	v_add_f32_e32 v53, 1.0, v64
	v_exp_f32_e32 v64, v50
	v_mul_f32_e32 v52, 0xbfb8aa3b, v52
	v_mul_f32_e32 v48, 0xbfb8aa3b, v48
	v_mul_f32_e32 v55, 0xbfb8aa3b, v55
	v_exp_f32_e32 v52, v52
	v_exp_f32_e32 v70, v48
	v_exp_f32_e32 v55, v55
	v_mul_f32_e32 v51, 0xbfb8aa3b, v51
	v_add_f32_e32 v50, 1.0, v54
	v_add_f32_e32 v54, 1.0, v64
	v_exp_f32_e32 v64, v51
	v_add_f32_e32 v48, 1.0, v52
	v_add_f32_e32 v52, 1.0, v70
	v_add_f32_e32 v51, 1.0, v55
	v_rcp_f32_e32 v48, v48
	v_rcp_f32_e32 v52, v52
	v_rcp_f32_e32 v49, v49
	v_rcp_f32_e32 v53, v53
	v_rcp_f32_e32 v50, v50
	v_rcp_f32_e32 v51, v51
	v_add_f32_e32 v55, 1.0, v64
	v_rcp_f32_e32 v54, v54
	v_rcp_f32_e32 v55, v55
	v_pk_mul_f32 v[48:49], v[60:61], v[48:49]
	v_pk_mul_f32 v[52:53], v[56:57], v[52:53]
	v_pk_mul_f32 v[50:51], v[62:63], v[50:51]
	v_pk_mul_f32 v[54:55], v[58:59], v[54:55]
	v_cvt_pk_bf16_f32 v48, v48, v49
	v_cvt_pk_bf16_f32 v49, v50, v51
	v_cvt_pk_bf16_f32 v50, v52, v53
	v_add_co_u32_e32 v52, vcc, s40, v112
	v_cvt_pk_bf16_f32 v51, v54, v55
	s_nop 0
	v_addc_co_u32_e32 v53, vcc, 0, v113, vcc
	v_mul_f32_e32 v37, 0xbfb8aa3b, v37
	v_mul_f32_e32 v33, 0xbfb8aa3b, v33
	global_store_dwordx4 v[52:53], v[48:51], off sc1
	v_exp_f32_e32 v37, v37
	v_mul_f32_e32 v38, 0xbfb8aa3b, v38
	v_exp_f32_e32 v48, v33
	v_mul_f32_e32 v34, 0xbfb8aa3b, v34
	v_add_f32_e32 v33, 1.0, v37
	v_exp_f32_e32 v38, v38
	v_add_f32_e32 v37, 1.0, v48
	v_exp_f32_e32 v48, v34
	v_mul_f32_e32 v36, 0xbfb8aa3b, v36
	v_mul_f32_e32 v32, 0xbfb8aa3b, v32
	v_mul_f32_e32 v39, 0xbfb8aa3b, v39
	v_exp_f32_e32 v36, v36
	v_exp_f32_e32 v54, v32
	v_exp_f32_e32 v39, v39
	v_mul_f32_e32 v35, 0xbfb8aa3b, v35
	v_add_f32_e32 v34, 1.0, v38
	v_add_f32_e32 v38, 1.0, v48
	v_exp_f32_e32 v48, v35
	v_add_f32_e32 v32, 1.0, v36
	v_add_f32_e32 v36, 1.0, v54
	v_add_f32_e32 v35, 1.0, v39
	v_rcp_f32_e32 v32, v32
	v_rcp_f32_e32 v36, v36
	v_rcp_f32_e32 v33, v33
	v_rcp_f32_e32 v37, v37
	v_rcp_f32_e32 v34, v34
	v_rcp_f32_e32 v35, v35
	v_add_f32_e32 v39, 1.0, v48
	v_rcp_f32_e32 v38, v38
	v_rcp_f32_e32 v39, v39
	v_pk_mul_f32 v[32:33], v[44:45], v[32:33]
	v_pk_mul_f32 v[36:37], v[40:41], v[36:37]
	v_pk_mul_f32 v[34:35], v[46:47], v[34:35]
	v_pk_mul_f32 v[38:39], v[42:43], v[38:39]
	v_cvt_pk_bf16_f32 v32, v32, v33
	v_cvt_pk_bf16_f32 v33, v34, v35
	v_cvt_pk_bf16_f32 v34, v36, v37
	v_add_co_u32_e32 v36, vcc, s41, v112
	v_cvt_pk_bf16_f32 v35, v38, v39
	s_nop 0
	v_addc_co_u32_e32 v37, vcc, 0, v113, vcc
	v_mul_f32_e32 v21, 0xbfb8aa3b, v21
	v_mul_f32_e32 v17, 0xbfb8aa3b, v17
	global_store_dwordx4 v[36:37], v[32:35], off sc1
	v_exp_f32_e32 v21, v21
	v_mul_f32_e32 v22, 0xbfb8aa3b, v22
	v_exp_f32_e32 v32, v17
	v_mul_f32_e32 v18, 0xbfb8aa3b, v18
	v_add_f32_e32 v17, 1.0, v21
	v_exp_f32_e32 v22, v22
	v_add_f32_e32 v21, 1.0, v32
	v_exp_f32_e32 v32, v18
	v_mul_f32_e32 v20, 0xbfb8aa3b, v20
	v_mul_f32_e32 v16, 0xbfb8aa3b, v16
	v_mul_f32_e32 v23, 0xbfb8aa3b, v23
	v_exp_f32_e32 v20, v20
	v_exp_f32_e32 v38, v16
	v_exp_f32_e32 v23, v23
	v_mul_f32_e32 v19, 0xbfb8aa3b, v19
	v_add_f32_e32 v18, 1.0, v22
	v_add_f32_e32 v22, 1.0, v32
	v_exp_f32_e32 v32, v19
	v_add_f32_e32 v16, 1.0, v20
	v_add_f32_e32 v20, 1.0, v38
	v_add_f32_e32 v19, 1.0, v23
	v_rcp_f32_e32 v16, v16
	v_rcp_f32_e32 v20, v20
	v_rcp_f32_e32 v17, v17
	v_rcp_f32_e32 v21, v21
	v_rcp_f32_e32 v18, v18
	v_rcp_f32_e32 v19, v19
	v_add_f32_e32 v23, 1.0, v32
	v_rcp_f32_e32 v22, v22
	v_rcp_f32_e32 v23, v23
	v_pk_mul_f32 v[16:17], v[28:29], v[16:17]
	v_pk_mul_f32 v[20:21], v[24:25], v[20:21]
	v_pk_mul_f32 v[18:19], v[30:31], v[18:19]
	v_pk_mul_f32 v[22:23], v[26:27], v[22:23]
	v_cvt_pk_bf16_f32 v16, v16, v17
	v_cvt_pk_bf16_f32 v17, v18, v19
	v_cvt_pk_bf16_f32 v18, v20, v21
	v_add_co_u32_e32 v20, vcc, s42, v112
	v_cvt_pk_bf16_f32 v19, v22, v23
	s_nop 0
	v_addc_co_u32_e32 v21, vcc, 0, v113, vcc
	v_mul_f32_e32 v5, 0xbfb8aa3b, v5
	v_mul_f32_e32 v1, 0xbfb8aa3b, v1
	global_store_dwordx4 v[20:21], v[16:19], off sc1
	v_exp_f32_e32 v5, v5
	v_mul_f32_e32 v6, 0xbfb8aa3b, v6
	v_exp_f32_e32 v16, v1
	v_mul_f32_e32 v2, 0xbfb8aa3b, v2
	v_add_f32_e32 v1, 1.0, v5
	v_exp_f32_e32 v6, v6
	v_add_f32_e32 v5, 1.0, v16
	v_exp_f32_e32 v16, v2
	v_mul_f32_e32 v4, 0xbfb8aa3b, v4
	v_mul_f32_e32 v0, 0xbfb8aa3b, v0
	v_mul_f32_e32 v7, 0xbfb8aa3b, v7
	v_exp_f32_e32 v4, v4
	v_exp_f32_e32 v22, v0
	v_exp_f32_e32 v7, v7
	v_mul_f32_e32 v3, 0xbfb8aa3b, v3
	v_add_f32_e32 v2, 1.0, v6
	v_add_f32_e32 v6, 1.0, v16
	v_exp_f32_e32 v16, v3
	v_add_f32_e32 v0, 1.0, v4
	v_add_f32_e32 v4, 1.0, v22
	v_add_f32_e32 v3, 1.0, v7
	v_rcp_f32_e32 v0, v0
	v_rcp_f32_e32 v4, v4
	v_rcp_f32_e32 v1, v1
	v_rcp_f32_e32 v5, v5
	v_rcp_f32_e32 v2, v2
	v_rcp_f32_e32 v3, v3
	v_add_f32_e32 v7, 1.0, v16
	v_rcp_f32_e32 v6, v6
	v_rcp_f32_e32 v7, v7
	v_pk_mul_f32 v[0:1], v[12:13], v[0:1]
	v_pk_mul_f32 v[4:5], v[8:9], v[4:5]
	v_pk_mul_f32 v[2:3], v[14:15], v[2:3]
	v_cvt_pk_bf16_f32 v0, v0, v1
	v_cvt_pk_bf16_f32 v1, v2, v3
	v_cvt_pk_bf16_f32 v2, v4, v5
	v_add_co_u32_e32 v4, vcc, 0x58000, v112
	v_pk_mul_f32 v[6:7], v[10:11], v[6:7]
	s_nop 0
	v_addc_co_u32_e32 v5, vcc, 0, v113, vcc
	v_cvt_pk_bf16_f32 v3, v6, v7
	s_andn2_b64 vcc, exec, s[4:5]
	s_mov_b64 s[4:5], -1
	global_store_dwordx4 v[4:5], v[0:3], off sc1
	s_cbranch_vccnz .LBB0_641
	s_andn2_b64 vcc, exec, s[6:7]
	s_cbranch_vccnz .LBB0_640
	s_barrier
	s_branch .LBB0_640
